# norm row loops: x rows prefetched two rows ahead (loop unrolled by two, two register buffers)
# baseline (speedup 1.0000x reference)
.LBB0_159:
	v_mov_b32_e32 v0, v188
	v_readlane_b32 s0, v253, 49
	v_ashrrev_i32_e32 v2, 6, v0
	s_mul_i32 s25, s58, 9
	v_add_u32_e32 v18, s0, v2
	s_movk_i32 s0, 0x4800
	v_cmp_gt_i32_e32 vcc, s0, v18
	s_and_saveexec_b64 s[34:35], vcc
	v_writelane_b32 v253, s58, 19
	s_cbranch_execz .LBB0_172
	s_cmp_eq_u32 s58, 0
	s_cselect_b64 s[36:37], -1, 0
	s_cmp_lg_u32 s58, 0
	v_readlane_b32 s0, v253, 19
	v_cmp_lt_i32_e32 vcc, v193, v192
	s_cselect_b64 s[38:39], -1, 0
	s_lshl_b32 s60, s0, 10
	v_readlane_b32 s40, v252, 18
	v_cndmask_b32_e32 v3, v191, v193, vcc
	v_cmp_lt_i32_e32 vcc, v194, v192
	s_lshl_b64 s[0:1], s[60:61], 2
	v_readlane_b32 s52, v252, 30
	v_lshlrev_b32_e32 v34, 2, v3
	v_cndmask_b32_e32 v3, v191, v194, vcc
	v_cmp_lt_i32_e32 vcc, v195, v192
	v_readlane_b32 s53, v252, 31
	s_add_u32 s0, s52, s0
	v_and_b32_e32 v2, 63, v0
	v_lshlrev_b32_e32 v35, 2, v3
	v_cndmask_b32_e32 v3, v191, v195, vcc
	v_cmp_lt_i32_e32 vcc, v196, v192
	s_addc_u32 s1, s53, s1
	v_lshlrev_b32_e32 v0, 4, v2
	v_lshlrev_b32_e32 v36, 2, v3
	v_cndmask_b32_e32 v3, v191, v196, vcc
	v_cmp_lt_i32_e32 vcc, v197, v192
	v_readlane_b32 s48, v252, 26
	v_readlane_b32 s49, v252, 27
	v_readlane_b32 s50, v252, 28
	v_readlane_b32 s51, v252, 29
	v_lshlrev_b32_e32 v4, 2, v2
	v_lshl_add_u64 v[20:21], s[0:1], 0, v[0:1]
	v_lshlrev_b32_e32 v37, 2, v3
	v_cndmask_b32_e32 v3, v191, v197, vcc
	v_cmp_lt_i32_e32 vcc, v198, v192
	v_readlane_b32 s0, v253, 40
	v_readlane_b32 s41, v252, 19
	v_readlane_b32 s48, v252, 14
	v_readlane_b32 s50, v251, 2
	v_readlane_b32 s22, v253, 47
	v_lshlrev_b32_e32 v38, 2, v3
	v_cndmask_b32_e32 v3, v191, v198, vcc
	v_or_b32_e32 v6, 0x100, v4
	v_or_b32_e32 v8, 0x200, v4
	v_or_b32_e32 v10, 0x300, v4
	v_lshl_add_u64 v[22:23], s[94:95], 0, v[0:1]
	v_lshlrev_b32_e32 v0, 3, v2
	v_readlane_b32 s1, v253, 41
	v_readlane_b32 s58, v253, 19
	s_mov_b32 s19, 0x800000
	v_readlane_b32 s49, v252, 15
	v_readlane_b32 s51, v251, 3
	v_readlane_b32 s23, v253, 48
	v_lshlrev_b32_e32 v39, 2, v3
	v_lshl_add_u64 v[24:25], s[0:1], 0, v[0:1]
	s_mov_b64 s[40:41], 0
	v_lshlrev_b32_e32 v0, 4, v2
	v_lshlrev_b32_e32 v26, 2, v4
	v_lshlrev_b32_e32 v28, 2, v6
	v_lshlrev_b32_e32 v30, 2, v8
	v_lshlrev_b32_e32 v32, 2, v10
	v_readlane_b32 s42, v252, 20
	v_readlane_b32 s43, v252, 21
	v_readlane_b32 s44, v252, 22
	v_readlane_b32 s45, v252, 23
	v_readlane_b32 s46, v252, 24
	v_readlane_b32 s47, v252, 25
	v_readlane_b32 s54, v252, 32
	v_readlane_b32 s55, v252, 33
	s_cmp_lg_u32 s58, 0
	s_cbranch_scc0 .LBB0_164
	v_and_b32_e32 v96, 63, v188
	v_lshlrev_b32_e32 v2, 4, v96
	v_lshlrev_b32_e32 v3, 3, v96
	v_lshlrev_b32_e32 v100, 2, v96
	v_xor_b32_e32 v4, 0x80, v100
	v_xor_b32_e32 v5, 0x40, v100
	v_xor_b32_e32 v6, 0x20, v100
	v_xor_b32_e32 v7, 0x10, v100
	v_xor_b32_e32 v8, 0x8, v100
	v_xor_b32_e32 v9, 0x4, v100
	v_readfirstlane_b32 s98, v18
	v_mov_b32_e32 v110, v24
	v_mov_b32_e32 v111, v25
	s_movk_i32 s99, 0x4800
	s_mul_i32 s0, s25, 0x6000
	s_add_u32 s100, s22, s0
	s_addc_u32 s101, s23, 0
	v_readfirstlane_b32 s0, v20
	v_readfirstlane_b32 s1, v21
	s_nop 4
	global_load_dwordx4 v[48:51], v2, s[0:1]
	global_load_dwordx4 v[52:55], v2, s[0:1] offset:1024
	global_load_dwordx4 v[56:59], v2, s[0:1] offset:2048
	global_load_dwordx4 v[60:63], v2, s[0:1] offset:3072
	s_lshl_b32 s2, s98, 12
	s_add_u32 s2, s94, s2
	s_addc_u32 s3, s95, 0
	global_load_dwordx4 v[32:35], v2, s[2:3]
	global_load_dwordx4 v[36:39], v2, s[2:3] offset:1024
	global_load_dwordx4 v[40:43], v2, s[2:3] offset:2048
	global_load_dwordx4 v[44:47], v2, s[2:3] offset:3072
	s_add_u32 s0, s98, s91
	s_cmp_lt_u32 s0, s99
	s_cselect_b32 s0, s0, s98
	s_lshl_b32 s0, s0, 12
	s_add_u32 s0, s94, s0
	s_addc_u32 s1, s95, 0
	global_load_dwordx4 v[112:115], v2, s[0:1]
	global_load_dwordx4 v[116:119], v2, s[0:1] offset:1024
	global_load_dwordx4 v[120:123], v2, s[0:1] offset:2048
	global_load_dwordx4 v[124:127], v2, s[0:1] offset:3072
	s_waitcnt vmcnt(4)
	s_branch .LnbodyA_0
.LntopA_0:
	s_waitcnt vmcnt(16)
.LnbodyA_0:
	v_mov_b32_e32 v16, v32
	v_mov_b32_e32 v17, v33
	v_mov_b32_e32 v18, v34
	v_mov_b32_e32 v19, v35
	v_mov_b32_e32 v20, v36
	v_mov_b32_e32 v21, v37
	v_mov_b32_e32 v22, v38
	v_mov_b32_e32 v23, v39
	v_mov_b32_e32 v24, v40
	v_mov_b32_e32 v25, v41
	v_mov_b32_e32 v26, v42
	v_mov_b32_e32 v27, v43
	v_mov_b32_e32 v28, v44
	v_mov_b32_e32 v29, v45
	v_mov_b32_e32 v30, v46
	v_mov_b32_e32 v31, v47
	s_min_u32 s0, s98, 0x4000
	s_lshr_b32 s0, s0, 11
	s_mul_i32 s0, s0, 0x6000
	s_add_u32 s2, s100, s0
	s_addc_u32 s3, s101, 0
	global_load_dwordx4 v[80:83], v2, s[2:3]
	global_load_dwordx4 v[84:87], v2, s[2:3] offset:1024
	global_load_dwordx4 v[88:91], v2, s[2:3] offset:2048
	global_load_dwordx4 v[92:95], v2, s[2:3] offset:3072
	s_add_u32 s0, s2, 0x1000
	s_addc_u32 s1, s3, 0
	global_load_dwordx4 v[64:67], v2, s[0:1]
	global_load_dwordx4 v[68:71], v2, s[0:1] offset:1024
	global_load_dwordx4 v[72:75], v2, s[0:1] offset:2048
	global_load_dwordx4 v[76:79], v2, s[0:1] offset:3072
	s_add_u32 s2, s98, s91
	s_add_u32 s0, s2, s91
	s_cmp_lt_u32 s0, s99
	s_cselect_b32 s0, s0, s98
	s_lshl_b32 s0, s0, 12
	s_add_u32 s0, s94, s0
	s_addc_u32 s1, s95, 0
	global_load_dwordx4 v[32:35], v2, s[0:1]
	global_load_dwordx4 v[36:39], v2, s[0:1] offset:1024
	global_load_dwordx4 v[40:43], v2, s[0:1] offset:2048
	global_load_dwordx4 v[44:47], v2, s[0:1] offset:3072
	v_mul_f32_e32 v97, v16, v16
	v_mul_f32_e32 v98, v20, v20
	v_mul_f32_e32 v99, v24, v24
	v_mul_f32_e32 v100, v28, v28
	v_fmac_f32_e32 v97, v17, v17
	v_fmac_f32_e32 v98, v21, v21
	v_fmac_f32_e32 v99, v25, v25
	v_fmac_f32_e32 v100, v29, v29
	v_fmac_f32_e32 v97, v18, v18
	v_fmac_f32_e32 v98, v22, v22
	v_fmac_f32_e32 v99, v26, v26
	v_fmac_f32_e32 v100, v30, v30
	v_fmac_f32_e32 v97, v19, v19
	v_fmac_f32_e32 v98, v23, v23
	v_fmac_f32_e32 v99, v27, v27
	v_fmac_f32_e32 v100, v31, v31
	v_add_f32_e32 v97, v97, v98
	v_add_f32_e32 v99, v99, v100
	v_add_f32_e32 v96, v97, v99
	ds_bpermute_b32 v97, v4, v96
	s_waitcnt lgkmcnt(0)
	v_add_f32_e32 v96, v96, v97
	ds_bpermute_b32 v97, v5, v96
	s_waitcnt lgkmcnt(0)
	v_add_f32_e32 v96, v96, v97
	ds_bpermute_b32 v97, v6, v96
	s_waitcnt lgkmcnt(0)
	v_add_f32_e32 v96, v96, v97
	ds_bpermute_b32 v97, v7, v96
	s_waitcnt lgkmcnt(0)
	v_add_f32_e32 v96, v96, v97
	ds_bpermute_b32 v97, v8, v96
	s_waitcnt lgkmcnt(0)
	v_add_f32_e32 v96, v96, v97
	ds_bpermute_b32 v97, v9, v96
	s_waitcnt lgkmcnt(0)
	v_add_f32_e32 v96, v96, v97
	v_fmamk_f32 v96, v96, 0x3a800000, v189
	v_rsq_f32_e32 v96, v96
	v_readfirstlane_b32 s0, v110
	v_readfirstlane_b32 s1, v111
	s_lshl_b32 s3, s98, 11
	s_add_u32 s0, s0, s3
	s_addc_u32 s1, s1, 0
	s_waitcnt vmcnt(4)
	v_mul_f32_e32 v16, v16, v96
	v_mul_f32_e32 v17, v17, v96
	v_mul_f32_e32 v18, v18, v96
	v_mul_f32_e32 v19, v19, v96
	v_mul_f32_e32 v20, v20, v96
	v_mul_f32_e32 v21, v21, v96
	v_mul_f32_e32 v22, v22, v96
	v_mul_f32_e32 v23, v23, v96
	v_mul_f32_e32 v24, v24, v96
	v_mul_f32_e32 v25, v25, v96
	v_mul_f32_e32 v26, v26, v96
	v_mul_f32_e32 v27, v27, v96
	v_mul_f32_e32 v28, v28, v96
	v_mul_f32_e32 v29, v29, v96
	v_mul_f32_e32 v30, v30, v96
	v_mul_f32_e32 v31, v31, v96
	v_mul_f32_e32 v16, v16, v48
	v_mul_f32_e32 v17, v17, v49
	v_mul_f32_e32 v18, v18, v50
	v_mul_f32_e32 v19, v19, v51
	v_mul_f32_e32 v20, v20, v52
	v_mul_f32_e32 v21, v21, v53
	v_mul_f32_e32 v22, v22, v54
	v_mul_f32_e32 v23, v23, v55
	v_mul_f32_e32 v24, v24, v56
	v_mul_f32_e32 v25, v25, v57
	v_mul_f32_e32 v26, v26, v58
	v_mul_f32_e32 v27, v27, v59
	v_mul_f32_e32 v28, v28, v60
	v_mul_f32_e32 v29, v29, v61
	v_mul_f32_e32 v30, v30, v62
	v_mul_f32_e32 v31, v31, v63
	v_add_f32_e32 v64, 1.0, v64
	v_add_f32_e32 v65, 1.0, v65
	v_add_f32_e32 v66, 1.0, v66
	v_add_f32_e32 v67, 1.0, v67
	v_add_f32_e32 v68, 1.0, v68
	v_add_f32_e32 v69, 1.0, v69
	v_add_f32_e32 v70, 1.0, v70
	v_add_f32_e32 v71, 1.0, v71
	v_add_f32_e32 v72, 1.0, v72
	v_add_f32_e32 v73, 1.0, v73
	v_add_f32_e32 v74, 1.0, v74
	v_add_f32_e32 v75, 1.0, v75
	v_add_f32_e32 v76, 1.0, v76
	v_add_f32_e32 v77, 1.0, v77
	v_add_f32_e32 v78, 1.0, v78
	v_add_f32_e32 v79, 1.0, v79
	v_fma_f32 v16, v16, v64, v80
	v_fma_f32 v17, v17, v65, v81
	v_fma_f32 v18, v18, v66, v82
	v_fma_f32 v19, v19, v67, v83
	v_fma_f32 v20, v20, v68, v84
	v_fma_f32 v21, v21, v69, v85
	v_fma_f32 v22, v22, v70, v86
	v_fma_f32 v23, v23, v71, v87
	v_fma_f32 v24, v24, v72, v88
	v_fma_f32 v25, v25, v73, v89
	v_fma_f32 v26, v26, v74, v90
	v_fma_f32 v27, v27, v75, v91
	v_fma_f32 v28, v28, v76, v92
	v_fma_f32 v29, v29, v77, v93
	v_fma_f32 v30, v30, v78, v94
	v_fma_f32 v31, v31, v79, v95
	v_cvt_pk_bf16_f32 v102, v16, v17
	v_cvt_pk_bf16_f32 v103, v18, v19
	v_cvt_pk_bf16_f32 v104, v20, v21
	v_cvt_pk_bf16_f32 v105, v22, v23
	v_cvt_pk_bf16_f32 v106, v24, v25
	v_cvt_pk_bf16_f32 v107, v26, v27
	v_cvt_pk_bf16_f32 v108, v28, v29
	v_cvt_pk_bf16_f32 v109, v30, v31
	global_store_dwordx2 v3, v[102:103], s[0:1]
	global_store_dwordx2 v3, v[104:105], s[0:1] offset:512
	global_store_dwordx2 v3, v[106:107], s[0:1] offset:1024
	global_store_dwordx2 v3, v[108:109], s[0:1] offset:1536
	s_mov_b32 s98, s2
	s_cmp_lt_u32 s98, s99
	s_cbranch_scc0 .Lnexit_0
	s_waitcnt vmcnt(16)
	v_mov_b32_e32 v16, v112
	v_mov_b32_e32 v17, v113
	v_mov_b32_e32 v18, v114
	v_mov_b32_e32 v19, v115
	v_mov_b32_e32 v20, v116
	v_mov_b32_e32 v21, v117
	v_mov_b32_e32 v22, v118
	v_mov_b32_e32 v23, v119
	v_mov_b32_e32 v24, v120
	v_mov_b32_e32 v25, v121
	v_mov_b32_e32 v26, v122
	v_mov_b32_e32 v27, v123
	v_mov_b32_e32 v28, v124
	v_mov_b32_e32 v29, v125
	v_mov_b32_e32 v30, v126
	v_mov_b32_e32 v31, v127
	s_min_u32 s0, s98, 0x4000
	s_lshr_b32 s0, s0, 11
	s_mul_i32 s0, s0, 0x6000
	s_add_u32 s2, s100, s0
	s_addc_u32 s3, s101, 0
	global_load_dwordx4 v[80:83], v2, s[2:3]
	global_load_dwordx4 v[84:87], v2, s[2:3] offset:1024
	global_load_dwordx4 v[88:91], v2, s[2:3] offset:2048
	global_load_dwordx4 v[92:95], v2, s[2:3] offset:3072
	s_add_u32 s0, s2, 0x1000
	s_addc_u32 s1, s3, 0
	global_load_dwordx4 v[64:67], v2, s[0:1]
	global_load_dwordx4 v[68:71], v2, s[0:1] offset:1024
	global_load_dwordx4 v[72:75], v2, s[0:1] offset:2048
	global_load_dwordx4 v[76:79], v2, s[0:1] offset:3072
	s_add_u32 s2, s98, s91
	s_add_u32 s0, s2, s91
	s_cmp_lt_u32 s0, s99
	s_cselect_b32 s0, s0, s98
	s_lshl_b32 s0, s0, 12
	s_add_u32 s0, s94, s0
	s_addc_u32 s1, s95, 0
	global_load_dwordx4 v[112:115], v2, s[0:1]
	global_load_dwordx4 v[116:119], v2, s[0:1] offset:1024
	global_load_dwordx4 v[120:123], v2, s[0:1] offset:2048
	global_load_dwordx4 v[124:127], v2, s[0:1] offset:3072
	v_mul_f32_e32 v97, v16, v16
	v_mul_f32_e32 v98, v20, v20
	v_mul_f32_e32 v99, v24, v24
	v_mul_f32_e32 v100, v28, v28
	v_fmac_f32_e32 v97, v17, v17
	v_fmac_f32_e32 v98, v21, v21
	v_fmac_f32_e32 v99, v25, v25
	v_fmac_f32_e32 v100, v29, v29
	v_fmac_f32_e32 v97, v18, v18
	v_fmac_f32_e32 v98, v22, v22
	v_fmac_f32_e32 v99, v26, v26
	v_fmac_f32_e32 v100, v30, v30
	v_fmac_f32_e32 v97, v19, v19
	v_fmac_f32_e32 v98, v23, v23
	v_fmac_f32_e32 v99, v27, v27
	v_fmac_f32_e32 v100, v31, v31
	v_add_f32_e32 v97, v97, v98
	v_add_f32_e32 v99, v99, v100
	v_add_f32_e32 v96, v97, v99
	ds_bpermute_b32 v97, v4, v96
	s_waitcnt lgkmcnt(0)
	v_add_f32_e32 v96, v96, v97
	ds_bpermute_b32 v97, v5, v96
	s_waitcnt lgkmcnt(0)
	v_add_f32_e32 v96, v96, v97
	ds_bpermute_b32 v97, v6, v96
	s_waitcnt lgkmcnt(0)
	v_add_f32_e32 v96, v96, v97
	ds_bpermute_b32 v97, v7, v96
	s_waitcnt lgkmcnt(0)
	v_add_f32_e32 v96, v96, v97
	ds_bpermute_b32 v97, v8, v96
	s_waitcnt lgkmcnt(0)
	v_add_f32_e32 v96, v96, v97
	ds_bpermute_b32 v97, v9, v96
	s_waitcnt lgkmcnt(0)
	v_add_f32_e32 v96, v96, v97
	v_fmamk_f32 v96, v96, 0x3a800000, v189
	v_rsq_f32_e32 v96, v96
	v_readfirstlane_b32 s0, v110
	v_readfirstlane_b32 s1, v111
	s_lshl_b32 s3, s98, 11
	s_add_u32 s0, s0, s3
	s_addc_u32 s1, s1, 0
	s_waitcnt vmcnt(4)
	v_mul_f32_e32 v16, v16, v96
	v_mul_f32_e32 v17, v17, v96
	v_mul_f32_e32 v18, v18, v96
	v_mul_f32_e32 v19, v19, v96
	v_mul_f32_e32 v20, v20, v96
	v_mul_f32_e32 v21, v21, v96
	v_mul_f32_e32 v22, v22, v96
	v_mul_f32_e32 v23, v23, v96
	v_mul_f32_e32 v24, v24, v96
	v_mul_f32_e32 v25, v25, v96
	v_mul_f32_e32 v26, v26, v96
	v_mul_f32_e32 v27, v27, v96
	v_mul_f32_e32 v28, v28, v96
	v_mul_f32_e32 v29, v29, v96
	v_mul_f32_e32 v30, v30, v96
	v_mul_f32_e32 v31, v31, v96
	v_mul_f32_e32 v16, v16, v48
	v_mul_f32_e32 v17, v17, v49
	v_mul_f32_e32 v18, v18, v50
	v_mul_f32_e32 v19, v19, v51
	v_mul_f32_e32 v20, v20, v52
	v_mul_f32_e32 v21, v21, v53
	v_mul_f32_e32 v22, v22, v54
	v_mul_f32_e32 v23, v23, v55
	v_mul_f32_e32 v24, v24, v56
	v_mul_f32_e32 v25, v25, v57
	v_mul_f32_e32 v26, v26, v58
	v_mul_f32_e32 v27, v27, v59
	v_mul_f32_e32 v28, v28, v60
	v_mul_f32_e32 v29, v29, v61
	v_mul_f32_e32 v30, v30, v62
	v_mul_f32_e32 v31, v31, v63
	v_add_f32_e32 v64, 1.0, v64
	v_add_f32_e32 v65, 1.0, v65
	v_add_f32_e32 v66, 1.0, v66
	v_add_f32_e32 v67, 1.0, v67
	v_add_f32_e32 v68, 1.0, v68
	v_add_f32_e32 v69, 1.0, v69
	v_add_f32_e32 v70, 1.0, v70
	v_add_f32_e32 v71, 1.0, v71
	v_add_f32_e32 v72, 1.0, v72
	v_add_f32_e32 v73, 1.0, v73
	v_add_f32_e32 v74, 1.0, v74
	v_add_f32_e32 v75, 1.0, v75
	v_add_f32_e32 v76, 1.0, v76
	v_add_f32_e32 v77, 1.0, v77
	v_add_f32_e32 v78, 1.0, v78
	v_add_f32_e32 v79, 1.0, v79
	v_fma_f32 v16, v16, v64, v80
	v_fma_f32 v17, v17, v65, v81
	v_fma_f32 v18, v18, v66, v82
	v_fma_f32 v19, v19, v67, v83
	v_fma_f32 v20, v20, v68, v84
	v_fma_f32 v21, v21, v69, v85
	v_fma_f32 v22, v22, v70, v86
	v_fma_f32 v23, v23, v71, v87
	v_fma_f32 v24, v24, v72, v88
	v_fma_f32 v25, v25, v73, v89
	v_fma_f32 v26, v26, v74, v90
	v_fma_f32 v27, v27, v75, v91
	v_fma_f32 v28, v28, v76, v92
	v_fma_f32 v29, v29, v77, v93
	v_fma_f32 v30, v30, v78, v94
	v_fma_f32 v31, v31, v79, v95
	v_cvt_pk_bf16_f32 v102, v16, v17
	v_cvt_pk_bf16_f32 v103, v18, v19
	v_cvt_pk_bf16_f32 v104, v20, v21
	v_cvt_pk_bf16_f32 v105, v22, v23
	v_cvt_pk_bf16_f32 v106, v24, v25
	v_cvt_pk_bf16_f32 v107, v26, v27
	v_cvt_pk_bf16_f32 v108, v28, v29
	v_cvt_pk_bf16_f32 v109, v30, v31
	global_store_dwordx2 v3, v[102:103], s[0:1]
	global_store_dwordx2 v3, v[104:105], s[0:1] offset:512
	global_store_dwordx2 v3, v[106:107], s[0:1] offset:1024
	global_store_dwordx2 v3, v[108:109], s[0:1] offset:1536
	s_mov_b32 s98, s2
	s_cmp_lt_u32 s98, s99
	s_cbranch_scc1 .LntopA_0
.Lnexit_0:
	s_branch .LBB0_172
.LBB0_161:
	s_or_b64 exec, exec, s[42:43]
	v_readlane_b32 s8, v253, 20
	v_readlane_b32 s10, v252, 8
	v_readlane_b32 s12, v253, 5
	v_readlane_b32 s14, v253, 17
	v_readlane_b32 s6, v253, 24
	v_readlane_b32 s4, v252, 10
	v_readlane_b32 s9, v253, 21
	v_readlane_b32 s11, v252, 9
	v_readlane_b32 s13, v253, 6
	v_readlane_b32 s15, v253, 18
	v_readlane_b32 s7, v253, 25
	v_readlane_b32 s5, v252, 11

.LBB0_943:
	s_or_b64 exec, exec, s[34:35]
	v_mov_b32_e32 v0, v188
	s_waitcnt lgkmcnt(0)
	s_barrier
	v_readlane_b32 s0, v253, 49
	v_ashrrev_i32_e32 v2, 6, v0
	s_nop 0
	v_add_u32_e32 v18, s0, v2
	v_cmp_gt_i32_e32 vcc, s22, v18
	s_and_saveexec_b64 s[34:35], vcc
	s_movk_i32 s26, 0x6000
	s_mov_b64 s[56:57], 0x4000
	s_cbranch_execz .LBB0_946
	v_readlane_b32 s40, v252, 18
	v_cmp_lt_i32_e32 vcc, v193, v192
	v_readlane_b32 s0, v253, 19
	v_readlane_b32 s48, v252, 26
	v_readlane_b32 s49, v252, 27
	v_readlane_b32 s50, v252, 28
	v_readlane_b32 s51, v252, 29
	v_readlane_b32 s52, v252, 30
	v_readlane_b32 s53, v252, 31
	v_cndmask_b32_e32 v4, v191, v193, vcc
	v_cmp_lt_i32_e32 vcc, v194, v192
	s_lshl_b32 s60, s0, 10
	v_readlane_b32 s54, v252, 32
	v_readlane_b32 s55, v252, 33
	s_mov_b64 s[48:49], s[52:53]
	v_lshlrev_b32_e32 v38, 2, v4
	v_cndmask_b32_e32 v4, v191, v194, vcc
	v_cmp_lt_i32_e32 vcc, v195, v192
	s_lshl_b64 s[0:1], s[60:61], 2
	s_mov_b64 s[50:51], s[54:55]
	v_lshlrev_b32_e32 v39, 2, v4
	v_cndmask_b32_e32 v4, v191, v195, vcc
	v_cmp_lt_i32_e32 vcc, v196, v192
	s_add_u32 s0, s50, s0
	v_and_b32_e32 v3, 63, v0
	v_lshlrev_b32_e32 v40, 2, v4
	v_cndmask_b32_e32 v4, v191, v196, vcc
	v_cmp_lt_i32_e32 vcc, v197, v192
	s_addc_u32 s1, s51, s1
	v_lshlrev_b32_e32 v0, 4, v3
	v_lshlrev_b32_e32 v41, 2, v4
	v_cndmask_b32_e32 v4, v191, v197, vcc
	v_cmp_lt_i32_e32 vcc, v198, v192
	v_lshlrev_b32_e32 v2, 2, v3
	v_lshl_add_u64 v[20:21], s[0:1], 0, v[0:1]
	v_lshlrev_b32_e32 v42, 2, v4
	v_cndmask_b32_e32 v4, v191, v198, vcc
	v_readlane_b32 s0, v253, 40
	v_readlane_b32 s41, v252, 19
	v_readlane_b32 s48, v252, 14
	v_readlane_b32 s50, v251, 2
	v_readlane_b32 s2, v253, 47
	v_lshlrev_b32_e32 v43, 2, v4
	v_or_b32_e32 v4, 0x100, v2
	v_or_b32_e32 v6, 0x200, v2
	v_or_b32_e32 v8, 0x300, v2
	v_lshl_add_u64 v[22:23], s[94:95], 0, v[0:1]
	v_lshlrev_b32_e32 v0, 3, v3
	v_readlane_b32 s1, v253, 41
	s_mov_b32 s27, s25
	v_readlane_b32 s58, v253, 19
	s_mov_b32 s19, 0x800000
	v_readlane_b32 s49, v252, 15
	v_readlane_b32 s51, v251, 3
	v_readlane_b32 s3, v253, 48
	v_lshl_add_u64 v[24:25], s[0:1], 0, v[0:1]
	s_mov_b64 s[40:41], 0
	v_lshlrev_b32_e32 v0, 2, v2
	v_lshlrev_b32_e32 v26, 2, v4
	v_lshlrev_b32_e32 v28, 2, v6
	v_lshlrev_b32_e32 v30, 2, v8
	v_readlane_b32 s42, v252, 20
	v_readlane_b32 s43, v252, 21
	v_readlane_b32 s44, v252, 22
	v_readlane_b32 s45, v252, 23
	v_readlane_b32 s46, v252, 24
	v_readlane_b32 s47, v252, 25
	v_and_b32_e32 v96, 63, v188
	v_lshlrev_b32_e32 v2, 4, v96
	v_lshlrev_b32_e32 v3, 3, v96
	v_lshlrev_b32_e32 v100, 2, v96
	v_xor_b32_e32 v4, 0x80, v100
	v_xor_b32_e32 v5, 0x40, v100
	v_xor_b32_e32 v6, 0x20, v100
	v_xor_b32_e32 v7, 0x10, v100
	v_xor_b32_e32 v8, 0x8, v100
	v_xor_b32_e32 v9, 0x4, v100
	v_readfirstlane_b32 s98, v18
	v_mov_b32_e32 v110, v24
	v_mov_b32_e32 v111, v25
	s_mov_b32 s99, s22
	s_mul_i32 s0, s27, 0x6000
	s_add_u32 s0, s0, 0x3000
	s_add_u32 s100, s2, s0
	s_addc_u32 s101, s3, 0
	v_readfirstlane_b32 s0, v20
	v_readfirstlane_b32 s1, v21
	s_nop 4
	global_load_dwordx4 v[48:51], v2, s[0:1]
	global_load_dwordx4 v[52:55], v2, s[0:1] offset:1024
	global_load_dwordx4 v[56:59], v2, s[0:1] offset:2048
	global_load_dwordx4 v[60:63], v2, s[0:1] offset:3072
	s_lshl_b32 s2, s98, 12
	s_add_u32 s2, s94, s2
	s_addc_u32 s3, s95, 0
	global_load_dwordx4 v[32:35], v2, s[2:3]
	global_load_dwordx4 v[36:39], v2, s[2:3] offset:1024
	global_load_dwordx4 v[40:43], v2, s[2:3] offset:2048
	global_load_dwordx4 v[44:47], v2, s[2:3] offset:3072
	s_add_u32 s0, s98, s91
	s_cmp_lt_u32 s0, s99
	s_cselect_b32 s0, s0, s98
	s_lshl_b32 s0, s0, 12
	s_add_u32 s0, s94, s0
	s_addc_u32 s1, s95, 0
	global_load_dwordx4 v[112:115], v2, s[0:1]
	global_load_dwordx4 v[116:119], v2, s[0:1] offset:1024
	global_load_dwordx4 v[120:123], v2, s[0:1] offset:2048
	global_load_dwordx4 v[124:127], v2, s[0:1] offset:3072
	s_waitcnt vmcnt(4)
	s_branch .LnbodyA_1

.Lnexit_1:
	s_branch .LBB0_946
.LBB0_946:
	s_or_b64 exec, exec, s[34:35]
	s_waitcnt vmcnt(0)
	v_readlane_b32 s56, v253, 4
	s_barrier
	s_mov_b64 s[34:35], exec
	v_readlane_b32 s0, v252, 12
	v_readlane_b32 s1, v252, 13
	s_and_b64 s[0:1], s[34:35], s[0:1]
	s_mov_b64 exec, s[0:1]
	s_cbranch_execz .LBB0_994
	v_readlane_b32 s0, v251, 0
	s_waitcnt vmcnt(0) expcnt(0) lgkmcnt(0)
	s_nop 0
	v_mov_b32_e32 v0, s0
	ds_read_b32 v3, v0
	v_readlane_b32 s0, v251, 1
	s_waitcnt lgkmcnt(0)
	v_cmp_ne_u32_e32 vcc, 0, v3
	v_mov_b32_e32 v0, s0
	ds_read_b32 v2, v0
	s_cbranch_vccnz .LBB0_962
	s_mov_b32 s2, 1
	s_branch .LBB0_950
